# v11 + P11 rmsnorm-scale block batched (8 loads, 2 LDS waits) + EpiAct second channel-group weights requested up front
# speedup vs baseline: 1.0114x; 1.0114x over previous
.LBB0_723:
	v_lshl_add_u32 v150, s6, 8, v186
	v_ashrrev_i32_e32 v151, 31, v150
	v_or_b32_e32 v102, 16, v150
	v_lshlrev_b64 v[92:93], 6, v[150:151]
	v_ashrrev_i32_e32 v103, 31, v102
	v_lshl_add_u64 v[92:93], v[140:141], 0, v[92:93]
	v_lshlrev_b64 v[102:103], 6, v[102:103]
	v_lshl_add_u64 v[102:103], v[140:141], 0, v[102:103]
	global_load_dwordx4 v[146:149], v[92:93], off
	global_load_dwordx4 v[174:177], v[102:103], off
	v_or_b32_e32 v92, 32, v150
	v_ashrrev_i32_e32 v93, 31, v92
	v_or_b32_e32 v102, 48, v150
	v_lshlrev_b64 v[92:93], 6, v[92:93]
	v_ashrrev_i32_e32 v103, 31, v102
	v_lshl_add_u64 v[92:93], v[140:141], 0, v[92:93]
	v_lshlrev_b64 v[102:103], 6, v[102:103]
	v_lshl_add_u64 v[102:103], v[140:141], 0, v[102:103]
	global_load_dwordx4 v[178:181], v[92:93], off
	global_load_dwordx4 v[182:185], v[102:103], off
	v_add_u32_e32 v92, 0x80, v150
	v_ashrrev_i32_e32 v93, 31, v92
	v_lshlrev_b64 v[92:93], 6, v[92:93]
	v_lshl_add_u64 v[92:93], v[140:141], 0, v[92:93]
	global_load_dwordx4 v[194:197], v[92:93], off
	v_add_u32_e32 v92, 0x90, v150
	v_ashrrev_i32_e32 v93, 31, v92
	v_lshlrev_b64 v[92:93], 6, v[92:93]
	v_lshl_add_u64 v[92:93], v[140:141], 0, v[92:93]
	global_load_dwordx4 v[198:201], v[92:93], off
	v_add_u32_e32 v92, 0xa0, v150
	v_ashrrev_i32_e32 v93, 31, v92
	v_add_u32_e32 v102, 0xb0, v150
	v_lshlrev_b64 v[92:93], 6, v[92:93]
	v_lshl_add_u64 v[92:93], v[140:141], 0, v[92:93]
	v_ashrrev_i32_e32 v103, 31, v102
	global_load_dwordx4 v[206:209], v[92:93], off
	v_lshlrev_b64 v[92:93], 6, v[102:103]
	v_lshl_add_u64 v[92:93], v[140:141], 0, v[92:93]
	global_load_dwordx4 v[210:213], v[92:93], off
	v_and_b32_e32 v168, 64, v191
	v_xor_b32_e32 v151, 16, v191
	v_add_u32_e32 v93, 64, v168
	v_xor_b32_e32 v92, 32, v191
	v_lshl_or_b32 v170, s46, 7, v188
	v_cmp_lt_i32_e32 vcc, v151, v93
	v_ashrrev_i32_e32 v171, 31, v170
	s_lshl_b32 s5, s6, 2
	v_cndmask_b32_e32 v102, v191, v151, vcc
	v_cmp_lt_i32_e32 vcc, v92, v93
	v_lshlrev_b32_e32 v151, 2, v102
	s_add_i32 s5, s5, s80
	v_cndmask_b32_e32 v103, v191, v92, vcc
	v_lshlrev_b64 v[92:93], 2, v[170:171]
	v_lshl_add_u64 v[172:173], s[30:31], 0, v[92:93]
	v_lshlrev_b32_e32 v193, 2, v103
	v_lshl_add_u64 v[102:103], s[0:1], 0, v[92:93]
	v_lshl_add_u64 v[202:203], s[48:49], 0, v[92:93]
	v_lshl_add_u64 v[168:169], s[82:83], 0, v[92:93]
	global_load_dwordx4 v[214:217], v[172:173], off
	global_load_dwordx4 v[218:221], v[102:103], off
	global_load_dwordx4 v[222:225], v[202:203], off
	global_load_dwordx4 v[226:229], v[168:169], off
	global_load_dwordx4 v[232:235], v[172:173], off offset:16
	global_load_dwordx4 v[236:239], v[102:103], off offset:16
	global_load_dwordx4 v[240:243], v[202:203], off offset:16
	global_load_dwordx4 v[244:247], v[168:169], off offset:16
	s_mul_hi_i32 s7, s5, 0x8400
	s_mul_i32 s5, s5, 0x8400
	s_add_u32 s6, s56, s5
	s_addc_u32 s7, s57, s7
	s_mov_b32 s5, 0
	s_mov_b32 s14, 0
	s_waitcnt vmcnt(0)
	v_mov_b32_e32 v92, v147
	v_mov_b32_e32 v93, v148
	v_mov_b32_e32 v147, v149
	v_mov_b32_e32 v102, v175
	v_mov_b32_e32 v103, v176
	v_mov_b32_e32 v175, v177
	v_pk_add_f32 v[92:93], v[92:93], v[146:147]
	v_pk_add_f32 v[102:103], v[102:103], v[174:175]
	v_mov_b32_e32 v175, v92
	v_mov_b32_e32 v174, v102
	v_mov_b32_e32 v92, v103
	v_pk_add_f32 v[92:93], v[174:175], v[92:93]
	ds_bpermute_b32 v103, v151, v93
	ds_bpermute_b32 v102, v151, v92
	v_mov_b32_e32 v146, v179
	v_mov_b32_e32 v147, v180
	v_mov_b32_e32 v179, v181
	v_mov_b32_e32 v148, v183
	s_waitcnt lgkmcnt(0)
	v_pk_add_f32 v[92:93], v[92:93], v[102:103]
	ds_bpermute_b32 v103, v193, v93
	ds_bpermute_b32 v102, v193, v92
	v_mov_b32_e32 v149, v184
	v_mov_b32_e32 v183, v185
	v_mov_b32_e32 v176, v195
	v_mov_b32_e32 v177, v196
	s_waitcnt lgkmcnt(0)
	v_pk_add_f32 v[92:93], v[92:93], v[102:103]
	v_mov_b32_e32 v195, v197
	v_pk_add_f32 v[146:147], v[146:147], v[178:179]
	v_pk_add_f32 v[148:149], v[148:149], v[182:183]
	v_pk_fma_f32 v[184:185], v[92:93], s[18:19], v[154:155] op_sel_hi:[1,0,0]
	v_pk_add_f32 v[174:175], v[176:177], v[194:195]
	v_mov_b32_e32 v176, v148
	v_mov_b32_e32 v177, v146
	v_mov_b32_e32 v146, v149
	v_mul_f32_e32 v92, 0x4b800000, v185
	v_cmp_gt_f32_e32 vcc, s84, v185
	v_pk_add_f32 v[146:147], v[176:177], v[146:147]
	ds_bpermute_b32 v149, v151, v147
	v_cndmask_b32_e32 v92, v185, v92, vcc
	ds_bpermute_b32 v148, v151, v146
	v_rsq_f32_e32 v92, v92
	v_mov_b32_e32 v180, v199
	v_mov_b32_e32 v181, v200
	v_mov_b32_e32 v199, v201
	v_mul_f32_e32 v93, 0x45800000, v92
	s_waitcnt lgkmcnt(0)
	v_pk_add_f32 v[102:103], v[146:147], v[148:149]
	v_cndmask_b32_e32 v148, v92, v93, vcc
	v_pk_add_f32 v[92:93], v[180:181], v[198:199]
	v_mov_b32_e32 v147, v174
	v_mov_b32_e32 v146, v92
	v_mov_b32_e32 v174, v93
	v_pk_add_f32 v[92:93], v[146:147], v[174:175]
	v_mov_b32_e32 v174, v207
	v_mov_b32_e32 v175, v208
	v_mov_b32_e32 v207, v209
	v_mov_b32_e32 v176, v211
	v_mov_b32_e32 v177, v212
	v_mov_b32_e32 v211, v213
	v_pk_add_f32 v[174:175], v[174:175], v[206:207]
	v_pk_add_f32 v[176:177], v[176:177], v[210:211]
	v_mov_b32_e32 v179, v174
	v_mov_b32_e32 v178, v176
	v_mov_b32_e32 v174, v177
	ds_bpermute_b32 v147, v151, v93
	ds_bpermute_b32 v146, v151, v92
	v_pk_add_f32 v[174:175], v[178:179], v[174:175]
	ds_bpermute_b32 v177, v151, v175
	ds_bpermute_b32 v176, v151, v174
	v_mov_b32_e32 v149, v148
	v_pk_mul_f32 v[128:129], v[128:129], v[148:149] op_sel_hi:[1,0]
	v_pk_mul_f32 v[230:231], v[130:131], v[148:149] op_sel_hi:[1,0]
	v_mul_f32_e32 v196, 0xbfb8aa3b, v222
	v_mov_b32_dpp v212, v128 row_ror:1 row_mask:0xf bank_mask:0xf bound_ctrl:1
	v_mul_f32_e32 v131, 0xbfb8aa3b, v226
	s_waitcnt lgkmcnt(2)
	v_pk_add_f32 v[178:179], v[92:93], v[146:147]
	v_mov_b32_dpp v213, v128 row_ror:2 row_mask:0xf bank_mask:0xf bound_ctrl:1
	v_cndmask_b32_e64 v92, v212, 0, s[36:37]
	v_mul_f32_e32 v194, 0xbfb8aa3b, v218
	v_fma_f32 v151, v196, v128, v131
	s_waitcnt lgkmcnt(0)
	v_pk_add_f32 v[174:175], v[174:175], v[176:177]
	v_lshl_add_u64 v[146:147], v[170:171], 1, s[6:7]
	v_mov_b32_dpp v210, v129 row_ror:1 row_mask:0xf bank_mask:0xf bound_ctrl:1
	v_cndmask_b32_e64 v93, 0, v213, s[38:39]
	v_mul_f32_e32 v185, 0xbfb8aa3b, v214
	v_fmac_f32_e32 v151, v194, v92
	v_mul_f32_e32 v199, 0xbfb8aa3b, v223
	v_mul_f32_e32 v171, 0xbfb8aa3b, v227
	ds_bpermute_b32 v183, v193, v103
	ds_bpermute_b32 v182, v193, v102
	ds_bpermute_b32 v181, v193, v179
	ds_bpermute_b32 v180, v193, v178
	ds_bpermute_b32 v177, v193, v175
	ds_bpermute_b32 v176, v193, v174
	v_mov_b32_dpp v211, v129 row_ror:2 row_mask:0xf bank_mask:0xf bound_ctrl:1
	v_fmac_f32_e32 v151, v185, v93
	v_cndmask_b32_e64 v193, v210, 0, s[36:37]
	v_mul_f32_e32 v197, 0xbfb8aa3b, v219
	v_fma_f32 v200, v199, v129, v171
	v_exp_f32_e32 v93, v151
	v_cndmask_b32_e64 v198, 0, v211, s[38:39]
	v_mul_f32_e32 v195, 0xbfb8aa3b, v215
	v_fmac_f32_e32 v200, v197, v193
	v_fmac_f32_e32 v200, v195, v198
	v_exp_f32_e32 v193, v200
	v_mul_f32_e32 v130, 0xbf317218, v148
	v_add_f32_e32 v93, 1.0, v93
	v_mul_f32_e32 v92, v124, v130
	v_rcp_f32_e32 v93, v93
	v_mul_f32_e32 v92, v92, v151
	v_add_f32_e32 v151, 1.0, v193
	v_rcp_f32_e32 v151, v151
	v_mul_f32_e32 v92, v92, v93
	v_mul_f32_e32 v93, v125, v130
	v_mul_f32_e32 v93, v93, v200
	v_mov_b32_dpp v208, v230 row_ror:1 row_mask:0xf bank_mask:0xf bound_ctrl:1
	v_mul_f32_e32 v93, v93, v151
	v_mul_f32_e32 v202, 0xbfb8aa3b, v224
	v_mul_f32_e32 v151, 0xbfb8aa3b, v228
	v_mov_b32_dpp v209, v230 row_ror:2 row_mask:0xf bank_mask:0xf bound_ctrl:1
	v_cndmask_b32_e64 v193, v208, 0, s[36:37]
	v_mul_f32_e32 v200, 0xbfb8aa3b, v220
	v_fma_f32 v214, v202, v230, v151
	v_mov_b32_dpp v206, v231 row_ror:1 row_mask:0xf bank_mask:0xf bound_ctrl:1
	v_cndmask_b32_e64 v201, 0, v209, s[38:39]
	v_mul_f32_e32 v198, 0xbfb8aa3b, v216
	v_fmac_f32_e32 v214, v200, v193
	v_mul_f32_e32 v205, 0xbfb8aa3b, v225
	v_mul_f32_e32 v193, 0xbfb8aa3b, v229
	v_mov_b32_dpp v207, v231 row_ror:2 row_mask:0xf bank_mask:0xf bound_ctrl:1
	v_fmac_f32_e32 v214, v198, v201
	v_cndmask_b32_e64 v218, v206, 0, s[36:37]
	v_mul_f32_e32 v201, 0xbfb8aa3b, v217
	v_mul_f32_e32 v203, 0xbfb8aa3b, v221
	v_fma_f32 v217, v205, v231, v193
	v_exp_f32_e32 v216, v214
	v_cndmask_b32_e64 v219, 0, v207, s[38:39]
	v_fmac_f32_e32 v217, v203, v218
	v_fmac_f32_e32 v217, v201, v219
	v_exp_f32_e32 v218, v217
	v_add_f32_e32 v216, 1.0, v216
	v_mul_f32_e32 v215, v126, v130
	v_rcp_f32_e32 v216, v216
	v_mul_f32_e32 v214, v215, v214
	v_add_f32_e32 v215, 1.0, v218
	v_rcp_f32_e32 v215, v215
	v_mul_f32_e32 v214, v214, v216
	v_mul_f32_e32 v216, v127, v130
	v_cmp_gt_f32_e64 s[46:47], s84, v184
	v_mul_f32_e32 v216, v216, v217
	v_mul_f32_e32 v215, v216, v215
	v_cvt_pk_bf16_f32 v92, v92, v93
	v_cvt_pk_bf16_f32 v93, v214, v215
	v_cvt_pk_bf16_f32 v128, v128, v129
	v_cvt_pk_bf16_f32 v129, v230, v231
	s_and_saveexec_b64 s[6:7], s[40:41]
	s_cbranch_execz .LBB0_725
	v_mov_b32_e32 v216, v148
	v_mov_b32_e32 v217, v148
	v_lshl_add_u64 v[214:215], v[146:147], 0, s[14:15]
	v_pk_mul_f32 v[126:127], v[126:127], v[216:217]
	v_pk_mul_f32 v[124:125], v[124:125], v[148:149]
	s_nop 0
	v_cvt_pk_bf16_f32 v124, v124, v125
	v_cvt_pk_bf16_f32 v125, v126, v127
	v_lshl_add_u64 v[126:127], v[214:215], 0, v[138:139]
	v_add_co_u32_e32 v214, vcc, 0x2000, v126
	s_nop 1
	v_addc_co_u32_e32 v215, vcc, 0, v127, vcc
	v_add_co_u32_e32 v126, vcc, 0x5000, v126
	global_store_dwordx2 v[214:215], v[128:129], off offset:3072
	s_nop 0
	v_addc_co_u32_e32 v127, vcc, 0, v127, vcc
	global_store_dwordx2 v[126:127], v[124:125], off offset:2048

.LBB0_731:
	s_or_b64 exec, exec, s[6:7]
	v_mad_u64_u32 v[66:67], s[6:7], v150, s67, v[170:171]
	v_lshl_add_u32 v71, v66, 1, -8
	v_or_b32_e32 v74, 4, v170
	v_ashrrev_i32_e32 v75, 31, v74
	v_lshlrev_b64 v[82:83], 2, v[74:75]
	v_lshl_add_u64 v[74:75], s[0:1], 0, v[82:83]
	v_lshl_add_u64 v[82:83], s[48:49], 0, v[82:83]
	v_mov_b64_e32 v[66:67], v[232:233]
	v_mov_b64_e32 v[68:69], v[234:235]
	v_pk_mul_f32 v[60:61], v[60:61], v[148:149]
	v_mov_b64_e32 v[74:75], v[236:237]
	v_mov_b64_e32 v[76:77], v[238:239]
	s_nop 0
	v_mov_b64_e32 v[82:83], v[240:241]
	v_mov_b64_e32 v[84:85], v[242:243]
	s_nop 0
	v_mov_b64_e32 v[86:87], v[244:245]
	v_mov_b64_e32 v[88:89], v[246:247]
	v_mov_b32_e32 v94, v148
	v_mov_b32_e32 v95, v148
	v_mov_b32_dpp v122, v60 row_ror:1 row_mask:0xf bank_mask:0xf bound_ctrl:1
	v_pk_mul_f32 v[62:63], v[62:63], v[94:95]
	v_mov_b32_dpp v123, v60 row_ror:2 row_mask:0xf bank_mask:0xf bound_ctrl:1
	v_cndmask_b32_e64 v94, v122, 0, s[36:37]
	v_cndmask_b32_e64 v95, 0, v123, s[38:39]
	v_mov_b32_dpp v119, v61 row_ror:1 row_mask:0xf bank_mask:0xf bound_ctrl:1
	v_mov_b32_dpp v121, v61 row_ror:2 row_mask:0xf bank_mask:0xf bound_ctrl:1
	v_mov_b32_dpp v105, v62 row_ror:1 row_mask:0xf bank_mask:0xf bound_ctrl:1
	v_mov_b32_dpp v118, v62 row_ror:2 row_mask:0xf bank_mask:0xf bound_ctrl:1
	v_mov_b32_dpp v91, v63 row_ror:1 row_mask:0xf bank_mask:0xf bound_ctrl:1
	v_mov_b32_dpp v104, v63 row_ror:2 row_mask:0xf bank_mask:0xf bound_ctrl:1
	s_mov_b32 s5, 8
	s_mov_b32 s14, 8
	v_mul_f32_e32 v79, 0xbfb8aa3b, v66
	v_mul_f32_e32 v115, 0xbfb8aa3b, v82
	v_mul_f32_e32 v66, 0xbfb8aa3b, v86
	v_mul_f32_e32 v114, 0xbfb8aa3b, v74
	v_fma_f32 v74, v115, v60, v66
	v_fmac_f32_e32 v74, v114, v94
	v_fmac_f32_e32 v74, v79, v95
	v_mul_f32_e32 v82, v56, v130
	v_mul_f32_e32 v82, v82, v74
	v_exp_f32_e32 v74, v74
	v_mul_f32_e32 v86, 0xbfb8aa3b, v67
	v_mul_f32_e32 v117, 0xbfb8aa3b, v83
	v_mul_f32_e32 v67, 0xbfb8aa3b, v87
	v_add_f32_e32 v74, 1.0, v74
	v_rcp_f32_e32 v74, v74
	v_mul_f32_e32 v116, 0xbfb8aa3b, v75
	v_fma_f32 v75, v117, v61, v67
	v_cndmask_b32_e64 v94, 0, v121, s[38:39]
	v_mul_f32_e32 v74, v82, v74
	v_cndmask_b32_e64 v82, v119, 0, s[36:37]
	v_fmac_f32_e32 v75, v116, v82
	v_fmac_f32_e32 v75, v86, v94
	v_mul_f32_e32 v82, v57, v130
	v_mul_f32_e32 v82, v82, v75
	v_exp_f32_e32 v75, v75
	v_mul_f32_e32 v87, 0xbfb8aa3b, v68
	v_mul_f32_e32 v84, 0xbfb8aa3b, v84
	v_mul_f32_e32 v68, 0xbfb8aa3b, v88
	v_add_f32_e32 v75, 1.0, v75
	v_rcp_f32_e32 v75, v75
	v_mul_f32_e32 v76, 0xbfb8aa3b, v76
	v_fma_f32 v88, v84, v62, v68
	v_cndmask_b32_e64 v83, 0, v118, s[38:39]
	v_mul_f32_e32 v75, v82, v75
	v_cndmask_b32_e64 v82, v105, 0, s[36:37]
	v_fmac_f32_e32 v88, v76, v82
	v_fmac_f32_e32 v88, v87, v83
	v_exp_f32_e32 v83, v88
	v_mul_f32_e32 v82, v58, v130
	v_mul_f32_e32 v82, v82, v88
	v_mul_f32_e32 v88, 0xbfb8aa3b, v69
	v_add_f32_e32 v83, 1.0, v83
	v_rcp_f32_e32 v83, v83
	v_mul_f32_e32 v85, 0xbfb8aa3b, v85
	v_mul_f32_e32 v69, 0xbfb8aa3b, v89
	v_mul_f32_e32 v77, 0xbfb8aa3b, v77
	v_mul_f32_e32 v82, v82, v83
	v_cndmask_b32_e64 v83, v91, 0, s[36:37]
	v_fma_f32 v89, v85, v63, v69
	v_cndmask_b32_e64 v94, 0, v104, s[38:39]
	v_fmac_f32_e32 v89, v77, v83
	v_fmac_f32_e32 v89, v88, v94
	v_mul_f32_e32 v83, v59, v130
	v_mul_f32_e32 v83, v83, v89
	v_exp_f32_e32 v89, v89
	v_cvt_pk_bf16_f32 v94, v74, v75
	s_nop 0
	v_add_f32_e32 v89, 1.0, v89
	v_rcp_f32_e32 v89, v89
	s_nop 0
	v_mul_f32_e32 v83, v83, v89
	v_cvt_pk_bf16_f32 v95, v82, v83
	v_cvt_pk_bf16_f32 v60, v60, v61
	v_cvt_pk_bf16_f32 v61, v62, v63
	s_and_saveexec_b64 s[6:7], s[38:39]
	s_xor_b64 s[6:7], exec, s[6:7]
	s_cbranch_execz .LBB0_733
	v_add_u32_e32 v60, s5, v71
	buffer_store_dwordx4 v[92:95], v60, s[52:55], 0 offen sc1

.LBB0_965:
	v_lshl_add_u32 v140, s26, 8, v143
	v_cndmask_b32_e64 v141, 0, 1, s[72:73]
	v_mov_b32_e32 v142, 1.0
	v_cmp_ne_u32_e64 s[38:39], 1, v141
	s_andn2_b64 vcc, exec, s[72:73]
	v_ashrrev_i32_e32 v141, 31, v140
	v_mov_b32_e32 v144, 1.0
	s_movk_i32 s40, 0xa00
	s_cbranch_vccnz .LBB0_967
	v_lshlrev_b64 v[150:151], 6, v[140:141]
	v_lshl_add_u64 v[150:151], v[134:135], 0, v[150:151]
	global_load_dwordx4 v[206:209], v[150:151], off
	global_load_dwordx4 v[210:213], v[150:151], off offset:1024
	global_load_dwordx4 v[214:217], v[150:151], off offset:2048
	global_load_dwordx4 v[218:221], v[150:151], off offset:3072
	v_add_co_u32_e32 v238, vcc, 0x2000, v150
	s_nop 1
	v_addc_co_u32_e32 v239, vcc, 0, v151, vcc
	global_load_dwordx4 v[222:225], v[238:239], off
	global_load_dwordx4 v[226:229], v[238:239], off offset:1024
	global_load_dwordx4 v[230:233], v[238:239], off offset:2048
	global_load_dwordx4 v[234:237], v[238:239], off offset:3072
	v_xor_b32_e32 v240, 16, v191
	v_xor_b32_e32 v241, 32, v191
	v_lshlrev_b32_e32 v240, 2, v240
	v_lshlrev_b32_e32 v241, 2, v241
	s_waitcnt vmcnt(0)
	v_add_f32_e32 v206, v207, v206
	v_add_f32_e32 v207, v208, v209
	v_add_f32_e32 v210, v211, v210
	v_add_f32_e32 v211, v212, v213
	v_add_f32_e32 v214, v215, v214
	v_add_f32_e32 v215, v216, v217
	v_add_f32_e32 v218, v219, v218
	v_add_f32_e32 v219, v220, v221
	v_add_f32_e32 v222, v223, v222
	v_add_f32_e32 v223, v224, v225
	v_add_f32_e32 v226, v227, v226
	v_add_f32_e32 v227, v228, v229
	v_add_f32_e32 v230, v231, v230
	v_add_f32_e32 v231, v232, v233
	v_add_f32_e32 v234, v235, v234
	v_add_f32_e32 v235, v236, v237
	v_add_f32_e32 v206, v206, v207
	v_add_f32_e32 v210, v210, v211
	v_add_f32_e32 v214, v214, v215
	v_add_f32_e32 v218, v218, v219
	v_add_f32_e32 v222, v222, v223
	v_add_f32_e32 v226, v226, v227
	v_add_f32_e32 v230, v230, v231
	v_add_f32_e32 v234, v234, v235
	ds_bpermute_b32 v207, v240, v206
	ds_bpermute_b32 v211, v240, v210
	ds_bpermute_b32 v215, v240, v214
	ds_bpermute_b32 v219, v240, v218
	ds_bpermute_b32 v223, v240, v222
	ds_bpermute_b32 v227, v240, v226
	ds_bpermute_b32 v231, v240, v230
	ds_bpermute_b32 v235, v240, v234
	s_waitcnt lgkmcnt(0)
	v_add_f32_e32 v206, v206, v207
	v_add_f32_e32 v210, v210, v211
	v_add_f32_e32 v214, v214, v215
	v_add_f32_e32 v218, v218, v219
	v_add_f32_e32 v222, v222, v223
	v_add_f32_e32 v226, v226, v227
	v_add_f32_e32 v230, v230, v231
	v_add_f32_e32 v234, v234, v235
	ds_bpermute_b32 v207, v241, v206
	ds_bpermute_b32 v211, v241, v210
	ds_bpermute_b32 v215, v241, v214
	ds_bpermute_b32 v219, v241, v218
	ds_bpermute_b32 v223, v241, v222
	ds_bpermute_b32 v227, v241, v226
	ds_bpermute_b32 v231, v241, v230
	ds_bpermute_b32 v235, v241, v234
	s_waitcnt lgkmcnt(0)
	v_add_f32_e32 v206, v206, v207
	v_add_f32_e32 v210, v210, v211
	v_add_f32_e32 v214, v214, v215
	v_add_f32_e32 v218, v218, v219
	v_add_f32_e32 v222, v222, v223
	v_add_f32_e32 v226, v226, v227
	v_add_f32_e32 v230, v230, v231
	v_add_f32_e32 v234, v234, v235
	v_fmamk_f32 v206, v206, 0x3a800000, v154
	v_cmp_gt_f32_e32 vcc, s84, v206
	v_mul_f32_e32 v207, 0x4b800000, v206
	s_nop 0
	v_cndmask_b32_e32 v206, v206, v207, vcc
	v_rsq_f32_e32 v206, v206
	s_nop 0
	v_mul_f32_e32 v207, 0x45800000, v206
	v_cndmask_b32_e32 v144, v206, v207, vcc
	v_fmamk_f32 v210, v210, 0x3a800000, v154
	v_cmp_gt_f32_e32 vcc, s84, v210
	v_mul_f32_e32 v211, 0x4b800000, v210
	s_nop 0
	v_cndmask_b32_e32 v210, v210, v211, vcc
	v_rsq_f32_e32 v210, v210
	s_nop 0
	v_mul_f32_e32 v211, 0x45800000, v210
	v_cndmask_b32_e32 v142, v210, v211, vcc
	v_fmamk_f32 v214, v214, 0x3a800000, v154
	v_cmp_gt_f32_e32 vcc, s84, v214
	v_mul_f32_e32 v215, 0x4b800000, v214
	s_nop 0
	v_cndmask_b32_e32 v214, v214, v215, vcc
	v_rsq_f32_e32 v214, v214
	s_nop 0
	v_mul_f32_e32 v215, 0x45800000, v214
	v_cndmask_b32_e32 v148, v214, v215, vcc
	v_fmamk_f32 v218, v218, 0x3a800000, v154
	v_cmp_gt_f32_e32 vcc, s84, v218
	v_mul_f32_e32 v219, 0x4b800000, v218
	s_nop 0
	v_cndmask_b32_e32 v218, v218, v219, vcc
	v_rsq_f32_e32 v218, v218
	s_nop 0
	v_mul_f32_e32 v219, 0x45800000, v218
	v_cndmask_b32_e32 v146, v218, v219, vcc
	v_fmamk_f32 v222, v222, 0x3a800000, v154
	v_cmp_gt_f32_e32 vcc, s84, v222
	v_mul_f32_e32 v223, 0x4b800000, v222
	s_nop 0
	v_cndmask_b32_e32 v222, v222, v223, vcc
	v_rsq_f32_e32 v222, v222
	s_nop 0
	v_mul_f32_e32 v223, 0x45800000, v222
	v_cndmask_b32_e32 v168, v222, v223, vcc
	v_fmamk_f32 v226, v226, 0x3a800000, v154
	v_cmp_gt_f32_e32 vcc, s84, v226
	v_mul_f32_e32 v227, 0x4b800000, v226
	s_nop 0
	v_cndmask_b32_e32 v226, v226, v227, vcc
	v_rsq_f32_e32 v226, v226
	s_nop 0
	v_mul_f32_e32 v227, 0x45800000, v226
	v_cndmask_b32_e32 v150, v226, v227, vcc
	v_fmamk_f32 v230, v230, 0x3a800000, v154
	v_cmp_gt_f32_e32 vcc, s84, v230
	v_mul_f32_e32 v231, 0x4b800000, v230
	s_nop 0
	v_cndmask_b32_e32 v230, v230, v231, vcc
	v_rsq_f32_e32 v230, v230
	s_nop 0
	v_mul_f32_e32 v231, 0x45800000, v230
	v_cndmask_b32_e32 v172, v230, v231, vcc
	v_fmamk_f32 v234, v234, 0x3a800000, v154
	v_cmp_gt_f32_e32 vcc, s84, v234
	v_mul_f32_e32 v235, 0x4b800000, v234
	s_nop 0
	v_cndmask_b32_e32 v234, v234, v235, vcc
	v_rsq_f32_e32 v234, v234
	s_nop 0
	v_mul_f32_e32 v235, 0x45800000, v234
	v_cndmask_b32_e32 v170, v234, v235, vcc
	s_branch .LBB0_981
.LBB0_967:
	v_mov_b32_e32 v146, 1.0
	v_mov_b32_e32 v148, 1.0
	v_mov_b32_e32 v150, 1.0
	v_mov_b32_e32 v168, 1.0
	v_mov_b32_e32 v170, 1.0
	v_mov_b32_e32 v172, 1.0
